# phase 5 row loop: the second half's gate chunk and norm weights loaded with the first batch (one memory wait per row instead of two plus a store round trip)
# speedup vs baseline: 1.0068x; 1.0068x over previous
; DI float bflo(unsigned u) { return __uint_as_float(u << 16); }
; DI float bfhi(unsigned u) { return __uint_as_float(u & 0xffff0000u); }
; DI void finalize_phase(const Params& p) {
;     ...
;             const int col = 512 * part + 8 * lane;
;             const u32x4 a = *(const u32x4*)(O0 + (size_t)row * 1024 + col), bq = *(const u32x4*)(O1 + (size_t)row * 1024 + col);
;             const u32x4 gt = *(const u32x4*)(P + (size_t)row * P2W + (part ? 2048 : 0) + 8 * lane);
;             float o[8], g[8];
;             o[0] = bflo(a.x) + bflo(bq.x); o[1] = bfhi(a.x) + bfhi(bq.x); o[2] = bflo(a.y) + bflo(bq.y); o[3] = bfhi(a.y) + bfhi(bq.y);
;             o[4] = bflo(a.z) + bflo(bq.z); o[5] = bfhi(a.z) + bfhi(bq.z); o[6] = bflo(a.w) + bflo(bq.w); o[7] = bfhi(a.w) + bfhi(bq.w);
;             g[0] = bflo(gt.x); g[1] = bfhi(gt.x); g[2] = bflo(gt.y); g[3] = bfhi(gt.y); g[4] = bflo(gt.z); g[5] = bfhi(gt.z); g[6] = bflo(gt.w); g[7] = bfhi(gt.w);
;             float ss = 0.f;
; #pragma unroll
;             for (int e = 0; e < 8; ++e) ss += o[e] * o[e];
;             ss += __shfl_xor(ss, 1); ss += __shfl_xor(ss, 2); ss += __shfl_xor(ss, 4); ss += __shfl_xor(ss, 8);
;             const float rstd = rsqrtf(ss * (1.f / 128.f) + EPS);
;             const float* nw = part ? p.ml_norm + 8 * lane : p.dn_norm + ((8 * lane) & 127);
;             const f32x4 n0 = *(const f32x4*)nw, n1 = *(const f32x4*)(nw + 4);
.LBB0_653:
	v_lshl_add_u64 v[38:39], v[18:19], 0, v[10:11]
	v_add_co_u32_e32 v22, vcc, 0x2376000, v38
	v_lshl_add_u64 v[24:25], v[16:17], 0, v[10:11]
	s_nop 0
	v_addc_co_u32_e32 v23, vcc, 0, v39, vcc
	v_add_co_u32_e32 v46, vcc, 0xa376000, v38
	v_add_co_u32_e64 v50, s[4:5], s23, v24
	s_nop 0
	v_addc_co_u32_e32 v47, vcc, 0, v39, vcc
	v_add_co_u32_e32 v24, vcc, 0x1ef76000, v24
	global_load_dwordx4 v[0:3], v[12:13], off offset:16
	global_load_dwordx4 v[4:7], v[12:13], off
	v_addc_co_u32_e64 v51, s[4:5], 0, v25, s[4:5]
	global_load_dwordx4 v[30:33], v[22:23], off
	global_load_dwordx4 v[34:37], v[22:23], off offset:1024
	global_load_dwordx4 v[38:41], v[46:47], off
	global_load_dwordx4 v[42:45], v[46:47], off offset:1024
	v_addc_co_u32_e32 v25, vcc, 0, v25, vcc
	global_load_dwordx4 v[46:49], v[24:25], off
	global_load_dwordx4 v[100:103], v[50:51], off
	global_load_dwordx4 v[104:107], v[14:15], off
	global_load_dwordx4 v[108:111], v[14:15], off offset:16
	v_add_u32_e32 v8, s12, v8
	v_lshl_add_u64 v[16:17], v[16:17], 0, s[14:15]
	v_lshl_add_u64 v[18:19], v[18:19], 0, s[16:17]
	s_waitcnt vmcnt(0)
	v_lshlrev_b32_e32 v24, 16, v33
	v_and_b32_e32 v25, 0xffff0000, v33
	v_lshlrev_b32_e32 v52, 16, v32
	v_and_b32_e32 v53, 0xffff0000, v32
	v_lshlrev_b32_e32 v32, 16, v31
	v_and_b32_e32 v33, 0xffff0000, v31
	v_lshlrev_b32_e32 v54, 16, v30
	v_and_b32_e32 v55, 0xffff0000, v30
	v_lshlrev_b32_e32 v30, 16, v37
	v_and_b32_e32 v31, 0xffff0000, v37
	v_lshlrev_b32_e32 v56, 16, v36
	v_and_b32_e32 v57, 0xffff0000, v36
	v_lshlrev_b32_e32 v36, 16, v35
	v_and_b32_e32 v37, 0xffff0000, v35
	v_lshlrev_b32_e32 v58, 16, v34
	v_and_b32_e32 v59, 0xffff0000, v34
	v_lshlrev_b32_e32 v34, 16, v41
	v_and_b32_e32 v35, 0xffff0000, v41
	v_lshlrev_b32_e32 v60, 16, v40
	v_and_b32_e32 v61, 0xffff0000, v40
	v_lshlrev_b32_e32 v40, 16, v39
	v_and_b32_e32 v41, 0xffff0000, v39
	v_lshlrev_b32_e32 v62, 16, v38
	v_and_b32_e32 v63, 0xffff0000, v38
	v_lshlrev_b32_e32 v38, 16, v45
	v_and_b32_e32 v39, 0xffff0000, v45
	v_lshlrev_b32_e32 v64, 16, v44
	v_and_b32_e32 v65, 0xffff0000, v44
	v_lshlrev_b32_e32 v44, 16, v43
	v_and_b32_e32 v45, 0xffff0000, v43
	v_lshlrev_b32_e32 v66, 16, v42
	v_and_b32_e32 v67, 0xffff0000, v42
	v_pk_add_f32 v[24:25], v[24:25], v[34:35]
	v_lshlrev_b32_e32 v34, 16, v49
	v_and_b32_e32 v35, 0xffff0000, v49
	v_pk_add_f32 v[42:43], v[52:53], v[60:61]
	v_lshlrev_b32_e32 v52, 16, v48
	v_and_b32_e32 v53, 0xffff0000, v48
	v_pk_add_f32 v[48:49], v[54:55], v[62:63]
	v_pk_add_f32 v[36:37], v[36:37], v[44:45]
	v_pk_add_f32 v[44:45], v[58:59], v[66:67]
	v_pk_add_f32 v[32:33], v[32:33], v[40:41]
	v_lshlrev_b32_e32 v40, 16, v47
	v_and_b32_e32 v41, 0xffff0000, v47
	v_lshlrev_b32_e32 v54, 16, v46
	v_and_b32_e32 v55, 0xffff0000, v46
	v_pk_add_f32 v[38:39], v[30:31], v[38:39]
	v_pk_add_f32 v[46:47], v[56:57], v[64:65]
	v_mov_b32_e32 v68, v45
	v_mov_b32_e32 v69, v49
	v_pk_mul_f32 v[30:31], v[24:25], v[24:25]
	v_pk_mul_f32 v[56:57], v[42:43], v[42:43]
	v_pk_mul_f32 v[58:59], v[32:33], v[32:33]
	v_mul_f32_e32 v70, 0xbfb8aa3b, v40
	v_mul_f32_e32 v71, 0xbfb8aa3b, v41
	v_pk_mul_f32 v[60:61], v[38:39], v[38:39]
	v_pk_mul_f32 v[62:63], v[46:47], v[46:47]
	v_pk_mul_f32 v[64:65], v[36:37], v[36:37]
	v_mov_b32_e32 v66, v44
	v_mov_b32_e32 v67, v48
	v_pk_mul_f32 v[68:69], v[68:69], v[68:69]
	v_exp_f32_e32 v76, v70
	v_exp_f32_e32 v77, v71
	v_mov_b32_e32 v70, v64
	v_mov_b32_e32 v71, v58
	v_mov_b32_e32 v58, v65
	v_mov_b32_e32 v64, v62
	v_mov_b32_e32 v65, v56
	v_mov_b32_e32 v56, v63
	v_mov_b32_e32 v62, v60
	v_mov_b32_e32 v63, v30
	v_mov_b32_e32 v30, v61
	v_pk_fma_f32 v[60:61], v[66:67], v[66:67], v[68:69]
	v_mul_f32_e32 v9, 0xbfb8aa3b, v52
	v_pk_add_f32 v[60:61], v[70:71], v[60:61]
	v_exp_f32_e32 v9, v9
	v_pk_add_f32 v[58:59], v[58:59], v[60:61]
	v_mul_f32_e32 v29, 0xbfb8aa3b, v53
	v_pk_add_f32 v[58:59], v[64:65], v[58:59]
	v_mul_f32_e32 v72, 0xbfb8aa3b, v54
	v_pk_add_f32 v[56:57], v[56:57], v[58:59]
	v_mul_f32_e32 v73, 0xbfb8aa3b, v55
	v_pk_add_f32 v[56:57], v[62:63], v[56:57]
	v_mul_f32_e32 v74, 0xbfb8aa3b, v34
	v_pk_add_f32 v[30:31], v[30:31], v[56:57]
	s_nop 1
	v_mov_b32_dpp v57, v31 quad_perm:[1,0,3,2] row_mask:0xf bank_mask:0xf
	s_nop 1
	v_mov_b32_dpp v56, v30 quad_perm:[1,0,3,2] row_mask:0xf bank_mask:0xf
	v_mul_f32_e32 v75, 0xbfb8aa3b, v35
	v_add_f32_e32 v9, 1.0, v9
	v_exp_f32_e32 v29, v29
	v_exp_f32_e32 v72, v72
	s_waitcnt lgkmcnt(0)
	v_pk_add_f32 v[30:31], v[30:31], v[56:57]
	s_nop 1
	v_mov_b32_dpp v57, v31 quad_perm:[2,3,0,1] row_mask:0xf bank_mask:0xf
	s_nop 1
	v_mov_b32_dpp v56, v30 quad_perm:[2,3,0,1] row_mask:0xf bank_mask:0xf
	v_exp_f32_e32 v73, v73
	v_exp_f32_e32 v74, v74
	v_exp_f32_e32 v75, v75
	v_rcp_f32_e32 v60, v9
	s_waitcnt lgkmcnt(0)
; DI unsigned pk2(float a, float b) { f32x2 v = {a, b}; bf16x2_t r = __builtin_convertvector(v, bf16x2_t); return __builtin_bit_cast(unsigned, r); }
; DI float sigmoidf_(float x) { return __builtin_amdgcn_rcpf(1.f + __expf(-x)); }
; DI float siluf_(float x) { return x * __builtin_amdgcn_rcpf(1.f + __expf(-x)); }
; DI void finalize_phase(const Params& p) {
;     ...
;             const float rstd = rsqrtf(ss * (1.f / 128.f) + EPS);
;             const float* nw = part ? p.ml_norm + 8 * lane : p.dn_norm + ((8 * lane) & 127);
;             const f32x4 n0 = *(const f32x4*)nw, n1 = *(const f32x4*)(nw + 4);
;             const float nn[8] = {n0.x, n0.y, n0.z, n0.w, n1.x, n1.y, n1.z, n1.w};
;             float y[8];
; #pragma unroll
;             for (int e = 0; e < 8; ++e) y[e] = o[e] * rstd * nn[e] * (part ? sigmoidf_(g[e]) : siluf_(g[e]));
;             u32x4 ov; ov.x = pk2(y[0], y[1]); ov.y = pk2(y[2], y[3]); ov.z = pk2(y[4], y[5]); ov.w = pk2(y[6], y[7]);
;             *(u32x4*)(O0 + (size_t)row * 1024 + col) = ov;
	v_pk_add_f32 v[30:31], v[30:31], v[56:57]
	s_nop 1
	v_mov_b32_dpp v57, v31 row_half_mirror row_mask:0xf bank_mask:0xf
	s_nop 1
	v_mov_b32_dpp v56, v30 row_half_mirror row_mask:0xf bank_mask:0xf
	v_add_f32_e32 v29, 1.0, v29
	v_add_f32_e32 v66, 1.0, v76
	v_add_f32_e32 v67, 1.0, v77
	v_add_f32_e32 v68, 1.0, v72
	s_waitcnt lgkmcnt(0)
	v_pk_add_f32 v[30:31], v[30:31], v[56:57]
	s_nop 1
	v_mov_b32_dpp v57, v31 row_ror:8 row_mask:0xf bank_mask:0xf
	s_nop 1
	v_mov_b32_dpp v56, v30 row_ror:8 row_mask:0xf bank_mask:0xf
	v_add_f32_e32 v69, 1.0, v73
	v_add_f32_e32 v70, 1.0, v74
	v_add_f32_e32 v71, 1.0, v75
	v_rcp_f32_e32 v61, v29
	s_waitcnt lgkmcnt(0)
	v_pk_add_f32 v[30:31], v[30:31], v[56:57]
	v_rcp_f32_e32 v64, v66
	v_pk_fma_f32 v[56:57], v[30:31], s[22:23], v[20:21] op_sel_hi:[1,0,0]
	v_rcp_f32_e32 v65, v67
	v_mul_f32_e32 v9, 0x4b800000, v57
	v_cmp_gt_f32_e32 vcc, s13, v57
	v_rcp_f32_e32 v66, v68
	v_rcp_f32_e32 v67, v69
	v_cndmask_b32_e32 v9, v57, v9, vcc
	v_rsq_f32_e32 v9, v9
	v_rcp_f32_e32 v68, v70
	v_rcp_f32_e32 v69, v71
	v_pk_mul_f32 v[52:53], v[60:61], v[52:53]
	v_mul_f32_e32 v29, 0x45800000, v9
	v_cndmask_b32_e32 v30, v9, v29, vcc
	v_pk_mul_f32 v[48:49], v[48:49], v[30:31] op_sel_hi:[1,0]
	v_pk_mul_f32 v[32:33], v[32:33], v[30:31] op_sel_hi:[1,0]
	v_pk_mul_f32 v[42:43], v[42:43], v[30:31] op_sel_hi:[1,0]
	v_pk_mul_f32 v[24:25], v[24:25], v[30:31] op_sel_hi:[1,0]
	v_pk_mul_f32 v[40:41], v[64:65], v[40:41]
	v_pk_mul_f32 v[54:55], v[66:67], v[54:55]
	v_pk_mul_f32 v[34:35], v[68:69], v[34:35]
	v_pk_mul_f32 v[4:5], v[4:5], v[48:49]
	v_pk_mul_f32 v[6:7], v[6:7], v[32:33]
	v_pk_mul_f32 v[0:1], v[0:1], v[42:43]
	v_pk_mul_f32 v[2:3], v[2:3], v[24:25]
	v_pk_mul_f32 v[4:5], v[54:55], v[4:5]
	v_pk_mul_f32 v[6:7], v[40:41], v[6:7]
	v_pk_mul_f32 v[24:25], v[52:53], v[0:1]
	v_pk_mul_f32 v[30:31], v[34:35], v[2:3]
	v_cvt_pk_bf16_f32 v0, v4, v5
	v_cvt_pk_bf16_f32 v1, v6, v7
	v_cvt_pk_bf16_f32 v2, v24, v25
	v_cvt_pk_bf16_f32 v3, v30, v31
	global_store_dwordx4 v[22:23], v[0:3], off
	s_nop 1
	v_mov_b64_e32 v[0:1], v[100:101]
	v_mov_b64_e32 v[2:3], v[102:103]
	v_mov_b64_e32 v[4:5], v[104:105]
	v_mov_b64_e32 v[6:7], v[106:107]
	v_mov_b64_e32 v[30:31], v[108:109]
	v_mov_b64_e32 v[32:33], v[110:111]
	s_nop 0
	v_cmp_lt_i32_e32 vcc, s24, v8
	s_or_b64 s[18:19], vcc, s[18:19]
	v_mul_f32_e32 v9, 0x4b800000, v56
	v_cmp_gt_f32_e32 vcc, s13, v56
	v_and_b32_e32 v29, 0xffff0000, v0
	s_nop 0
	v_cndmask_b32_e32 v9, v56, v9, vcc
	v_rsq_f32_e32 v9, v9
	v_lshlrev_b32_e32 v42, 16, v2
	v_and_b32_e32 v43, 0xffff0000, v2
	v_mul_f32_e32 v24, 0x45800000, v9
	v_cndmask_b32_e32 v24, v9, v24, vcc
	v_pk_mul_f32 v[34:35], v[44:45], v[24:25] op_sel_hi:[1,0]
	v_pk_mul_f32 v[36:37], v[36:37], v[24:25] op_sel_hi:[1,0]
	v_pk_mul_f32 v[40:41], v[46:47], v[24:25] op_sel_hi:[1,0]
	v_pk_mul_f32 v[24:25], v[38:39], v[24:25] op_sel_hi:[1,0]
	v_lshlrev_b32_e32 v9, 16, v0
	v_lshlrev_b32_e32 v38, 16, v1
	v_and_b32_e32 v39, 0xffff0000, v1
	v_lshlrev_b32_e32 v44, 16, v3
	v_and_b32_e32 v45, 0xffff0000, v3
	v_pk_mul_f32 v[0:1], v[4:5], v[34:35]
	v_pk_mul_f32 v[2:3], v[6:7], v[36:37]
	v_pk_mul_f32 v[4:5], v[30:31], v[40:41]
	v_pk_mul_f32 v[6:7], v[32:33], v[24:25]
	v_mul_f32_e32 v9, 0xbfb8aa3b, v9
	v_mul_f32_e32 v24, 0xbfb8aa3b, v29
	v_mul_f32_e32 v25, 0xbfb8aa3b, v38
	v_mul_f32_e32 v29, 0xbfb8aa3b, v39
	v_mul_f32_e32 v30, 0xbfb8aa3b, v42
	v_mul_f32_e32 v31, 0xbfb8aa3b, v43
	v_mul_f32_e32 v32, 0xbfb8aa3b, v44
	v_mul_f32_e32 v33, 0xbfb8aa3b, v45
	v_exp_f32_e32 v9, v9
	v_exp_f32_e32 v24, v24
	v_exp_f32_e32 v25, v25
	v_exp_f32_e32 v29, v29
	v_exp_f32_e32 v30, v30
	v_exp_f32_e32 v31, v31
	v_exp_f32_e32 v32, v32
	v_exp_f32_e32 v33, v33
	v_add_f32_e32 v9, 1.0, v9
	v_add_f32_e32 v34, 1.0, v24
	v_add_f32_e32 v35, 1.0, v25
	v_add_f32_e32 v29, 1.0, v29
	v_add_f32_e32 v36, 1.0, v30
	v_add_f32_e32 v37, 1.0, v31
	v_add_f32_e32 v38, 1.0, v32
	v_add_f32_e32 v39, 1.0, v33
	v_rcp_f32_e32 v24, v9
	v_rcp_f32_e32 v25, v34
	v_rcp_f32_e32 v30, v35
	v_rcp_f32_e32 v31, v29
	v_rcp_f32_e32 v32, v36
	v_rcp_f32_e32 v33, v37
	v_rcp_f32_e32 v34, v38
	v_rcp_f32_e32 v35, v39
	v_pk_mul_f32 v[0:1], v[24:25], v[0:1]
	v_pk_mul_f32 v[2:3], v[30:31], v[2:3]
	v_pk_mul_f32 v[4:5], v[32:33], v[4:5]
	v_pk_mul_f32 v[6:7], v[34:35], v[6:7]
	v_cvt_pk_bf16_f32 v0, v0, v1
	v_cvt_pk_bf16_f32 v1, v2, v3
	v_cvt_pk_bf16_f32 v2, v4, v5
	v_cvt_pk_bf16_f32 v3, v6, v7
	global_store_dwordx4 v[22:23], v[0:3], off offset:1024
	s_andn2_b64 exec, exec, s[18:19]
	s_cbranch_execnz .LBB0_653
